# split-K partial epilogue: f32 tiles staged through the per-wave LDS tile, each store writes 8 full 128-byte lines
# speedup vs baseline: 1.0055x; 1.0055x over previous
.LBB0_988:
	v_and_b32_e32 v158, 63, v186
	v_lshrrev_b32_e32 v159, 6, v186
	v_lshlrev_b32_e32 v159, 11, v159
	v_add_u32_e32 v159, 0x20100, v159
	v_lshl_add_u32 v157, v158, 4, v159
	v_and_b32_e32 v160, 15, v137
	v_lshl_add_u32 v156, v160, 7, v159
	v_and_b32_e32 v161, 12, v98
	v_lshl_add_u32 v156, v161, 2, v156
	v_lshrrev_b32_e32 v162, 3, v158
	v_sub_u32_e32 v162, v162, v160
	v_lshlrev_b32_e32 v162, 12, v162
	v_and_b32_e32 v163, 7, v158
	v_lshlrev_b32_e32 v163, 2, v163
	v_sub_u32_e32 v163, v163, v161
	v_lshlrev_b32_e32 v163, 2, v163
	v_add_u32_e32 v150, v162, v163
	v_ashrrev_i32_e32 v151, 31, v150
	v_mov_b32_e32 v152, 0x8000
	v_mov_b32_e32 v153, 0
	s_abs_i32 s13, s63
	s_mul_hi_u32 s15, s13, s61
	s_mul_i32 s20, s15, s56
	s_ashr_i32 s11, s63, 31
	s_sub_i32 s13, s13, s20
	s_xor_b32 s11, s11, s57
	s_add_i32 s20, s15, 1
	s_sub_i32 s21, s13, s56
	s_cmp_ge_u32 s13, s56
	s_cselect_b32 s15, s20, s15
	s_cselect_b32 s13, s21, s13
	s_add_i32 s20, s15, 1
	s_cmp_ge_u32 s13, s56
	s_cselect_b32 s13, s20, s15
	s_xor_b32 s13, s13, s11
	s_sub_i32 s20, s13, s11
	s_ashr_i32 s21, s20, 31
	s_lshl_b64 s[20:21], s[20:21], 23
	s_add_u32 s20, s51, s20
	s_addc_u32 s21, s52, s21
	s_lshl_b32 s10, s10, 8
	v_lshl_or_b32 v146, s16, 8, v98
	v_add_u32_e32 v148, s10, v137
	v_ashrrev_i32_e32 v147, 31, v146
	v_lshl_add_u64 v[146:147], v[146:147], 2, s[20:21]
	v_ashrrev_i32_e32 v149, 31, v148
	v_lshlrev_b64 v[148:149], 12, v[148:149]
	v_lshl_add_u64 v[148:149], v[146:147], 0, v[148:149]
	v_lshl_add_u64 v[148:149], v[150:151], 0, v[148:149]
	v_lshl_add_u64 v[154:155], v[148:149], 0, v[152:153]
	ds_write_b128 v156, v[128:131]
	ds_write_b128 v156, v[124:127] offset:64
	ds_read_b128 v[128:131], v157
	ds_read_b128 v[124:127], v157 offset:1024
	ds_write_b128 v156, v[120:123]
	ds_write_b128 v156, v[116:119] offset:64
	ds_read_b128 v[120:123], v157
	ds_read_b128 v[116:119], v157 offset:1024
	s_waitcnt lgkmcnt(0)
	global_store_dwordx4 v[148:149], v[128:131], off
	global_store_dwordx4 v[154:155], v[124:127], off
	global_store_dwordx4 v[148:149], v[120:123], off offset:512
	global_store_dwordx4 v[154:155], v[116:119], off offset:512
	s_and_b64 vcc, exec, s[38:39]
	s_nop 0
	v_add_u32_e32 v116, s10, v138
	s_nop 0
	v_ashrrev_i32_e32 v117, 31, v116
	v_lshlrev_b64 v[116:117], 12, v[116:117]
	v_lshl_add_u64 v[116:117], v[146:147], 0, v[116:117]
	v_lshl_add_u64 v[116:117], v[150:151], 0, v[116:117]
	v_lshl_add_u64 v[154:155], v[116:117], 0, v[152:153]
	ds_write_b128 v156, v[112:115]
	ds_write_b128 v156, v[108:111] offset:64
	ds_read_b128 v[112:115], v157
	ds_read_b128 v[108:111], v157 offset:1024
	ds_write_b128 v156, v[104:107]
	ds_write_b128 v156, v[100:103] offset:64
	ds_read_b128 v[104:107], v157
	ds_read_b128 v[100:103], v157 offset:1024
	s_waitcnt lgkmcnt(0)
	global_store_dwordx4 v[116:117], v[112:115], off
	global_store_dwordx4 v[154:155], v[108:111], off
	global_store_dwordx4 v[116:117], v[104:107], off offset:512
	global_store_dwordx4 v[154:155], v[100:103], off offset:512
	s_nop 1
	v_add_u32_e32 v100, s10, v139
	s_nop 0
	v_ashrrev_i32_e32 v101, 31, v100
	v_lshlrev_b64 v[100:101], 12, v[100:101]
	v_lshl_add_u64 v[100:101], v[146:147], 0, v[100:101]
	v_lshl_add_u64 v[100:101], v[150:151], 0, v[100:101]
	v_lshl_add_u64 v[154:155], v[100:101], 0, v[152:153]
	ds_write_b128 v156, v[92:95]
	ds_write_b128 v156, v[88:91] offset:64
	ds_read_b128 v[92:95], v157
	ds_read_b128 v[88:91], v157 offset:1024
	ds_write_b128 v156, v[84:87]
	ds_write_b128 v156, v[80:83] offset:64
	ds_read_b128 v[84:87], v157
	ds_read_b128 v[80:83], v157 offset:1024
	s_waitcnt lgkmcnt(0)
	global_store_dwordx4 v[100:101], v[92:95], off
	global_store_dwordx4 v[154:155], v[88:91], off
	global_store_dwordx4 v[100:101], v[84:87], off offset:512
	global_store_dwordx4 v[154:155], v[80:83], off offset:512
	s_nop 1
	v_add_u32_e32 v80, s10, v140
	s_nop 0
	v_ashrrev_i32_e32 v81, 31, v80
	v_lshlrev_b64 v[80:81], 12, v[80:81]
	v_lshl_add_u64 v[80:81], v[146:147], 0, v[80:81]
	v_lshl_add_u64 v[80:81], v[150:151], 0, v[80:81]
	v_lshl_add_u64 v[154:155], v[80:81], 0, v[152:153]
	ds_write_b128 v156, v[76:79]
	ds_write_b128 v156, v[72:75] offset:64
	ds_read_b128 v[76:79], v157
	ds_read_b128 v[72:75], v157 offset:1024
	ds_write_b128 v156, v[68:71]
	ds_write_b128 v156, v[64:67] offset:64
	ds_read_b128 v[68:71], v157
	ds_read_b128 v[64:67], v157 offset:1024
	s_waitcnt lgkmcnt(0)
	global_store_dwordx4 v[80:81], v[76:79], off
	global_store_dwordx4 v[154:155], v[72:75], off
	global_store_dwordx4 v[80:81], v[68:71], off offset:512
	global_store_dwordx4 v[154:155], v[64:67], off offset:512
	s_nop 1
	v_add_u32_e32 v64, s10, v141
	s_nop 0
	v_ashrrev_i32_e32 v65, 31, v64
	v_lshlrev_b64 v[64:65], 12, v[64:65]
	v_lshl_add_u64 v[64:65], v[146:147], 0, v[64:65]
	v_lshl_add_u64 v[64:65], v[150:151], 0, v[64:65]
	v_lshl_add_u64 v[154:155], v[64:65], 0, v[152:153]
	ds_write_b128 v156, v[60:63]
	ds_write_b128 v156, v[56:59] offset:64
	ds_read_b128 v[60:63], v157
	ds_read_b128 v[56:59], v157 offset:1024
	ds_write_b128 v156, v[52:55]
	ds_write_b128 v156, v[48:51] offset:64
	ds_read_b128 v[52:55], v157
	ds_read_b128 v[48:51], v157 offset:1024
	s_waitcnt lgkmcnt(0)
	global_store_dwordx4 v[64:65], v[60:63], off
	global_store_dwordx4 v[154:155], v[56:59], off
	global_store_dwordx4 v[64:65], v[52:55], off offset:512
	global_store_dwordx4 v[154:155], v[48:51], off offset:512
	s_nop 1
	v_add_u32_e32 v48, s10, v142
	s_nop 0
	v_ashrrev_i32_e32 v49, 31, v48
	v_lshlrev_b64 v[48:49], 12, v[48:49]
	v_lshl_add_u64 v[48:49], v[146:147], 0, v[48:49]
	v_lshl_add_u64 v[48:49], v[150:151], 0, v[48:49]
	v_lshl_add_u64 v[154:155], v[48:49], 0, v[152:153]
	ds_write_b128 v156, v[44:47]
	ds_write_b128 v156, v[40:43] offset:64
	ds_read_b128 v[44:47], v157
	ds_read_b128 v[40:43], v157 offset:1024
	ds_write_b128 v156, v[36:39]
	ds_write_b128 v156, v[32:35] offset:64
	ds_read_b128 v[36:39], v157
	ds_read_b128 v[32:35], v157 offset:1024
	s_waitcnt lgkmcnt(0)
	global_store_dwordx4 v[48:49], v[44:47], off
	global_store_dwordx4 v[154:155], v[40:43], off
	global_store_dwordx4 v[48:49], v[36:39], off offset:512
	global_store_dwordx4 v[154:155], v[32:35], off offset:512
	s_nop 1
	v_add_u32_e32 v32, s10, v143
	s_nop 0
	v_ashrrev_i32_e32 v33, 31, v32
	v_lshlrev_b64 v[32:33], 12, v[32:33]
	v_lshl_add_u64 v[32:33], v[146:147], 0, v[32:33]
	v_lshl_add_u64 v[32:33], v[150:151], 0, v[32:33]
	v_lshl_add_u64 v[154:155], v[32:33], 0, v[152:153]
	ds_write_b128 v156, v[28:31]
	ds_write_b128 v156, v[24:27] offset:64
	ds_read_b128 v[28:31], v157
	ds_read_b128 v[24:27], v157 offset:1024
	ds_write_b128 v156, v[20:23]
	ds_write_b128 v156, v[16:19] offset:64
	ds_read_b128 v[20:23], v157
	ds_read_b128 v[16:19], v157 offset:1024
	s_waitcnt lgkmcnt(0)
	global_store_dwordx4 v[32:33], v[28:31], off
	global_store_dwordx4 v[154:155], v[24:27], off
	global_store_dwordx4 v[32:33], v[20:23], off offset:512
	global_store_dwordx4 v[154:155], v[16:19], off offset:512
	s_nop 1
	v_add_u32_e32 v16, s10, v144
	s_mov_b64 s[10:11], -1
	v_ashrrev_i32_e32 v17, 31, v16
	v_lshlrev_b64 v[16:17], 12, v[16:17]
	v_lshl_add_u64 v[16:17], v[146:147], 0, v[16:17]
	v_lshl_add_u64 v[16:17], v[150:151], 0, v[16:17]
	v_lshl_add_u64 v[154:155], v[16:17], 0, v[152:153]
	ds_write_b128 v156, v[12:15]
	ds_write_b128 v156, v[8:11] offset:64
	ds_read_b128 v[12:15], v157
	ds_read_b128 v[8:11], v157 offset:1024
	ds_write_b128 v156, v[4:7]
	ds_write_b128 v156, v[0:3] offset:64
	ds_read_b128 v[4:7], v157
	ds_read_b128 v[0:3], v157 offset:1024
	s_waitcnt lgkmcnt(0)
	global_store_dwordx4 v[16:17], v[12:15], off
	global_store_dwordx4 v[154:155], v[8:11], off
	global_store_dwordx4 v[16:17], v[4:7], off offset:512
	global_store_dwordx4 v[154:155], v[0:3], off offset:512
	s_cbranch_vccnz .LBB0_976
	s_andn2_b64 vcc, exec, s[0:1]
	s_cbranch_vccnz .LBB0_975
	s_barrier
	s_branch .LBB0_975
